# FFN1/FFN2 K-loops: per-segment s_setprio 1/0 flips removed (A/B test)
# baseline (speedup 1.0000x reference)
; #define PG8_STAGE(bufoff, gbase, voff) do { _Pragma("unroll") for (int _i = 0; _i < 2; ++_i) \
;         __builtin_amdgcn_global_load_lds((const unsigned*)((const char*)(gbase) + (voff)[_i]), (LAS unsigned*)(lds + (bufoff) + ldsw + _i * 8192), 16, 0, 0); } while (0)
; #define PG8_LDA(dst, b, h) do { _Pragma("unroll") for (int m = 0; m < 4; ++m) _Pragma("unroll") for (int k = 0; k < 2; ++k) dst[m][k] = *(const LAS bf16x8*)(lds + PG8_SA(b, h) + aoff + m * 2048 + k * 1024); } while (0)
; #define PG8_LDB(dst, b, h) do { _Pragma("unroll") for (int n = 0; n < 2; ++n) _Pragma("unroll") for (int k = 0; k < 2; ++k) dst[n][k] = *(const LAS bf16x8*)(lds + PG8_SB(b, h) + boff + n * 2048 + k * 1024); } while (0)
; #define PG8_MMA(ai, bj, At, Bt) do { __builtin_amdgcn_s_setprio(1); _Pragma("unroll") for (int m = 0; m < 4; ++m) _Pragma("unroll") for (int n = 0; n < 2; ++n) _Pragma("unroll") for (int k = 0; k < 2; ++k) \
;         acc[ai][bj][m][n] = __builtin_amdgcn_mfma_f32_16x16x32_bf16(Bt[n][k], At[m][k], acc[ai][bj][m][n], 0, 0, 0); __builtin_amdgcn_s_setprio(0); } while (0)
; #define PG8_WAIT_V(n) asm volatile("s_waitcnt vmcnt(" #n ")" ::: "memory")
; #define PG8_WAIT_L(n) asm volatile("s_waitcnt lgkmcnt(" #n ")" ::: "memory")
; #define PG8_BAR __builtin_amdgcn_s_barrier()
; template <class Epi, class Sched, bool ALIGN_EPI = true, bool SP2 = true, class Pre = NoPre>
; __device__ __forceinline__ void gemm_phase(LAS unsigned char* lds, const Gemm g, const Sched& S, const Epi& E, const Pre& pre = Pre()) {
;     ...
;             const bool last = (t == nt - 2);
;             const char* a1 = cA + (size_t)(t + 1) * kstep;
;             const char* a2 = last ? nA : cA + (size_t)(t + 2) * kstep; const char* b2 = last ? nB : cB + (size_t)(t + 2) * kstep;
;             const char* a3 = a2 + kstep; const char* b3 = b2 + kstep;
;             if constexpr (SP2) {
;             PG8_LDB(B0, 0, 0); PG8_LDB(B1, 0, 1); PG8_SCHED; PG8_LDA(At, 0, 0); PG8_STAGE(PG8_SA(1, 1), a1 + hsA, voffA);
;             PG8_WAIT_V(8); PG8_WAIT_L(0); PG8_BAR; PG8_MMA(0, 0, At, B0); PG8_MMA(0, 1, At, B1); PG8_BAR; PG8_SCHED;
;             PG8_LDA(At, 0, 1); PG8_STAGE(PG8_SB(0, 0), b2, voffB); PG8_STAGE(PG8_SB(0, 1), b2 + hsB, voffB); PG8_STAGE(PG8_SA(0, 0), a2, voffA);
;             PG8_WAIT_V(8); PG8_WAIT_L(0); PG8_BAR; PG8_MMA(1, 0, At, B0); PG8_MMA(1, 1, At, B1); PG8_BAR; PG8_SCHED;
.LBB0_858:
	s_add_u32 s10, s30, 0xfffc0080
	s_addc_u32 s11, s31, -1
	s_add_i32 s80, 0, 0x10000
	s_cmp_eq_u32 s58, 12
	s_cselect_b32 s39, s21, s11
	s_cselect_b32 s38, s45, s10
	s_cselect_b32 s11, s17, s53
	s_cselect_b32 s10, s46, s47
	s_add_i32 s82, 0, 0x14000
	v_add_u32_e32 v156, s80, v138
	v_add_u32_e32 v172, s82, v138
	ds_read_b128 v[144:147], v156
	ds_read_b128 v[148:151], v156 offset:1024
	ds_read_b128 v[152:155], v156 offset:2048
	ds_read_b128 v[156:159], v156 offset:3072
	ds_read_b128 v[160:163], v172
	ds_read_b128 v[164:167], v172 offset:1024
	ds_read_b128 v[168:171], v172 offset:2048
	ds_read_b128 v[172:175], v172 offset:3072
	v_lshl_add_u64 v[220:221], s[30:31], 0, v[136:137]
	s_add_i32 m0, s8, 0xc000
	ds_read_b128 v[176:179], v143
	ds_read_b128 v[180:183], v143 offset:1024
	ds_read_b128 v[184:187], v143 offset:2048
	ds_read_b128 v[188:191], v143 offset:3072
	ds_read_b128 v[192:195], v143 offset:4096
	ds_read_b128 v[196:199], v143 offset:5120
	ds_read_b128 v[212:215], v143 offset:6144
	ds_read_b128 v[216:219], v143 offset:7168
	global_load_lds_dwordx4 v[220:221], off
	v_lshl_add_u64 v[220:221], s[30:31], 0, v[134:135]
	s_add_i32 m0, s8, 0xe000
	s_nop 0
	global_load_lds_dwordx4 v[220:221], off
	s_waitcnt vmcnt(8)
	s_waitcnt lgkmcnt(0)
	s_barrier
	s_waitcnt lgkmcnt(0)
	v_mfma_f32_16x16x32_bf16 v[124:127], v[144:147], v[176:179], v[124:127]
	v_mfma_f32_16x16x32_bf16 v[120:123], v[152:155], v[176:179], v[120:123]
	v_mfma_f32_16x16x32_bf16 v[108:111], v[144:147], v[184:187], v[108:111]
	v_mfma_f32_16x16x32_bf16 v[104:107], v[152:155], v[184:187], v[104:107]
	v_mfma_f32_16x16x32_bf16 v[92:95], v[144:147], v[192:195], v[92:95]
	v_mfma_f32_16x16x32_bf16 v[88:91], v[152:155], v[192:195], v[88:91]
	v_mfma_f32_16x16x32_bf16 v[76:79], v[144:147], v[212:215], v[76:79]
	v_mfma_f32_16x16x32_bf16 v[72:75], v[152:155], v[212:215], v[72:75]
	v_mfma_f32_16x16x32_bf16 v[124:127], v[148:151], v[180:183], v[124:127]
	v_mfma_f32_16x16x32_bf16 v[120:123], v[156:159], v[180:183], v[120:123]
	v_mfma_f32_16x16x32_bf16 v[108:111], v[148:151], v[188:191], v[108:111]
	v_mfma_f32_16x16x32_bf16 v[104:107], v[156:159], v[188:191], v[104:107]
	v_mfma_f32_16x16x32_bf16 v[92:95], v[148:151], v[196:199], v[92:95]
	v_mfma_f32_16x16x32_bf16 v[88:91], v[156:159], v[196:199], v[88:91]
	v_mfma_f32_16x16x32_bf16 v[76:79], v[148:151], v[216:219], v[76:79]
	v_mfma_f32_16x16x32_bf16 v[72:75], v[156:159], v[216:219], v[72:75]
	v_mfma_f32_16x16x32_bf16 v[116:119], v[160:163], v[176:179], v[116:119]
	v_mfma_f32_16x16x32_bf16 v[112:115], v[168:171], v[176:179], v[112:115]
	v_mfma_f32_16x16x32_bf16 v[100:103], v[160:163], v[184:187], v[100:103]
	v_mfma_f32_16x16x32_bf16 v[96:99], v[168:171], v[184:187], v[96:99]
	v_mfma_f32_16x16x32_bf16 v[84:87], v[160:163], v[192:195], v[84:87]
	v_mfma_f32_16x16x32_bf16 v[80:83], v[168:171], v[192:195], v[80:83]
	v_mfma_f32_16x16x32_bf16 v[68:71], v[160:163], v[212:215], v[68:71]
	v_mfma_f32_16x16x32_bf16 v[64:67], v[168:171], v[212:215], v[64:67]
	v_mfma_f32_16x16x32_bf16 v[116:119], v[164:167], v[180:183], v[116:119]
	v_mfma_f32_16x16x32_bf16 v[112:115], v[172:175], v[180:183], v[112:115]
	v_mfma_f32_16x16x32_bf16 v[100:103], v[164:167], v[188:191], v[100:103]
	v_mfma_f32_16x16x32_bf16 v[96:99], v[172:175], v[188:191], v[96:99]
	v_mfma_f32_16x16x32_bf16 v[84:87], v[164:167], v[196:199], v[84:87]
	v_mfma_f32_16x16x32_bf16 v[80:83], v[172:175], v[196:199], v[80:83]
	v_mfma_f32_16x16x32_bf16 v[68:71], v[164:167], v[216:219], v[68:71]
	v_mfma_f32_16x16x32_bf16 v[64:67], v[172:175], v[216:219], v[64:67]
	s_barrier
	s_add_i32 s80, s80, s7
	v_lshl_add_u64 v[220:221], s[10:11], 0, v[200:201]
	s_mov_b32 m0, s80
	ds_read_b128 v[176:179], v143 offset:16384
	ds_read_b128 v[180:183], v143 offset:17408
	ds_read_b128 v[184:187], v143 offset:18432
	ds_read_b128 v[188:191], v143 offset:19456
	ds_read_b128 v[192:195], v143 offset:20480
	ds_read_b128 v[196:199], v143 offset:21504
	ds_read_b128 v[212:215], v143 offset:22528
	ds_read_b128 v[216:219], v143 offset:23552
	global_load_lds_dwordx4 v[220:221], off
	s_add_i32 m0, s80, 0x2000
	s_add_u32 s80, s10, 0x40000
	v_lshl_add_u64 v[222:223], s[10:11], 0, v[128:129]
	s_addc_u32 s81, s11, 0
	s_add_i32 s82, s82, s7
	global_load_lds_dwordx4 v[222:223], off
	v_lshl_add_u64 v[224:225], s[80:81], 0, v[200:201]
	s_mov_b32 m0, s82
	v_lshl_add_u64 v[226:227], s[38:39], 0, v[130:131]
	global_load_lds_dwordx4 v[224:225], off
	v_lshl_add_u64 v[224:225], s[80:81], 0, v[128:129]
	s_add_i32 m0, s82, 0x2000
	s_nop 0
	global_load_lds_dwordx4 v[224:225], off
	v_lshl_add_u64 v[224:225], s[38:39], 0, v[132:133]
	s_mov_b32 m0, s8
	s_nop 0
	global_load_lds_dwordx4 v[224:225], off
	s_mov_b32 m0, s9
	s_nop 0
	global_load_lds_dwordx4 v[226:227], off
	s_waitcnt vmcnt(8)
	s_waitcnt lgkmcnt(0)
	s_barrier
; #define PG8_STAGE(bufoff, gbase, voff) do { _Pragma("unroll") for (int _i = 0; _i < 2; ++_i) \
;         __builtin_amdgcn_global_load_lds((const unsigned*)((const char*)(gbase) + (voff)[_i]), (LAS unsigned*)(lds + (bufoff) + ldsw + _i * 8192), 16, 0, 0); } while (0)
; #define PG8_LDA(dst, b, h) do { _Pragma("unroll") for (int m = 0; m < 4; ++m) _Pragma("unroll") for (int k = 0; k < 2; ++k) dst[m][k] = *(const LAS bf16x8*)(lds + PG8_SA(b, h) + aoff + m * 2048 + k * 1024); } while (0)
; #define PG8_LDB(dst, b, h) do { _Pragma("unroll") for (int n = 0; n < 2; ++n) _Pragma("unroll") for (int k = 0; k < 2; ++k) dst[n][k] = *(const LAS bf16x8*)(lds + PG8_SB(b, h) + boff + n * 2048 + k * 1024); } while (0)
; #define PG8_MMA(ai, bj, At, Bt) do { __builtin_amdgcn_s_setprio(1); _Pragma("unroll") for (int m = 0; m < 4; ++m) _Pragma("unroll") for (int n = 0; n < 2; ++n) _Pragma("unroll") for (int k = 0; k < 2; ++k) \
;         acc[ai][bj][m][n] = __builtin_amdgcn_mfma_f32_16x16x32_bf16(Bt[n][k], At[m][k], acc[ai][bj][m][n], 0, 0, 0); __builtin_amdgcn_s_setprio(0); } while (0)
; #define PG8_WAIT_V(n) asm volatile("s_waitcnt vmcnt(" #n ")" ::: "memory")
; #define PG8_WAIT_L(n) asm volatile("s_waitcnt lgkmcnt(" #n ")" ::: "memory")
; #define PG8_BAR __builtin_amdgcn_s_barrier()
; #define PG8_SCHED __builtin_amdgcn_sched_barrier(0)
; template <class Epi, class Sched, bool ALIGN_EPI = true, bool SP2 = true, class Pre = NoPre>
; __device__ __forceinline__ void gemm_phase(LAS unsigned char* lds, const Gemm g, const Sched& S, const Epi& E, const Pre& pre = Pre()) {
;     ...
;             PG8_WAIT_V(8); PG8_WAIT_L(0); PG8_BAR; PG8_MMA(1, 0, At, B0); PG8_MMA(1, 1, At, B1); PG8_BAR; PG8_SCHED;
;             PG8_LDB(B0, 1, 0); PG8_LDB(B1, 1, 1); PG8_SCHED; PG8_LDA(At, 1, 0); PG8_STAGE(PG8_SA(0, 1), a2 + hsA, voffA);
;             PG8_WAIT_V(8); PG8_WAIT_L(0); PG8_BAR; PG8_MMA(0, 0, At, B0); PG8_MMA(0, 1, At, B1); PG8_BAR; PG8_SCHED;
	s_waitcnt lgkmcnt(0)
	v_mfma_f32_16x16x32_bf16 v[60:63], v[144:147], v[176:179], v[60:63]
	v_mfma_f32_16x16x32_bf16 v[56:59], v[152:155], v[176:179], v[56:59]
	v_mfma_f32_16x16x32_bf16 v[52:55], v[144:147], v[184:187], v[52:55]
	v_mfma_f32_16x16x32_bf16 v[44:47], v[152:155], v[184:187], v[44:47]
	v_mfma_f32_16x16x32_bf16 v[36:39], v[144:147], v[192:195], v[36:39]
	v_mfma_f32_16x16x32_bf16 v[28:31], v[152:155], v[192:195], v[28:31]
	v_mfma_f32_16x16x32_bf16 v[16:19], v[144:147], v[212:215], v[16:19]
	v_mfma_f32_16x16x32_bf16 v[8:11], v[152:155], v[212:215], v[8:11]
	v_mfma_f32_16x16x32_bf16 v[60:63], v[148:151], v[180:183], v[60:63]
	v_mfma_f32_16x16x32_bf16 v[56:59], v[156:159], v[180:183], v[56:59]
	v_mfma_f32_16x16x32_bf16 v[52:55], v[148:151], v[188:191], v[52:55]
	v_mfma_f32_16x16x32_bf16 v[44:47], v[156:159], v[188:191], v[44:47]
	v_mfma_f32_16x16x32_bf16 v[36:39], v[148:151], v[196:199], v[36:39]
	v_mfma_f32_16x16x32_bf16 v[28:31], v[156:159], v[196:199], v[28:31]
	v_mfma_f32_16x16x32_bf16 v[16:19], v[148:151], v[216:219], v[16:19]
	v_mfma_f32_16x16x32_bf16 v[8:11], v[156:159], v[216:219], v[8:11]
	v_mfma_f32_16x16x32_bf16 v[48:51], v[160:163], v[176:179], v[48:51]
	v_mfma_f32_16x16x32_bf16 v[40:43], v[168:171], v[176:179], v[40:43]
	v_mfma_f32_16x16x32_bf16 v[32:35], v[160:163], v[184:187], v[32:35]
	v_mfma_f32_16x16x32_bf16 v[24:27], v[168:171], v[184:187], v[24:27]
	v_mfma_f32_16x16x32_bf16 v[20:23], v[160:163], v[192:195], v[20:23]
	v_mfma_f32_16x16x32_bf16 v[12:15], v[168:171], v[192:195], v[12:15]
	v_mfma_f32_16x16x32_bf16 v[4:7], v[160:163], v[212:215], v[4:7]
	v_mfma_f32_16x16x32_bf16 v[0:3], v[168:171], v[212:215], v[0:3]
	v_mfma_f32_16x16x32_bf16 v[48:51], v[164:167], v[180:183], v[48:51]
	v_mfma_f32_16x16x32_bf16 v[40:43], v[172:175], v[180:183], v[40:43]
	v_mfma_f32_16x16x32_bf16 v[32:35], v[164:167], v[188:191], v[32:35]
	v_mfma_f32_16x16x32_bf16 v[24:27], v[172:175], v[188:191], v[24:27]
	v_mfma_f32_16x16x32_bf16 v[20:23], v[164:167], v[196:199], v[20:23]
	v_mfma_f32_16x16x32_bf16 v[12:15], v[172:175], v[196:199], v[12:15]
	v_mfma_f32_16x16x32_bf16 v[4:7], v[164:167], v[216:219], v[4:7]
	v_mfma_f32_16x16x32_bf16 v[0:3], v[172:175], v[216:219], v[0:3]
	s_barrier
	s_add_i32 s80, 0, 0x18000
	s_add_i32 s81, 0, 0x1c000
	v_add_u32_e32 v156, s80, v138
	v_add_u32_e32 v172, s81, v138
	ds_read_b128 v[144:147], v156
	ds_read_b128 v[148:151], v156 offset:1024
	ds_read_b128 v[152:155], v156 offset:2048
	ds_read_b128 v[156:159], v156 offset:3072
	ds_read_b128 v[160:163], v172
	ds_read_b128 v[164:167], v172 offset:1024
	ds_read_b128 v[168:171], v172 offset:2048
	ds_read_b128 v[172:175], v172 offset:3072
	s_add_u32 s38, s38, 0x40000
	s_addc_u32 s39, s39, 0
	s_mov_b32 m0, s15
	v_lshl_add_u64 v[228:229], s[38:39], 0, v[132:133]
	ds_read_b128 v[176:179], v143 offset:32768
	ds_read_b128 v[180:183], v143 offset:33792
	ds_read_b128 v[184:187], v143 offset:34816
	ds_read_b128 v[188:191], v143 offset:35840
	ds_read_b128 v[192:195], v143 offset:36864
	ds_read_b128 v[196:199], v143 offset:37888
	ds_read_b128 v[212:215], v143 offset:38912
	ds_read_b128 v[216:219], v143 offset:39936
	global_load_lds_dwordx4 v[228:229], off
	v_lshl_add_u64 v[228:229], s[38:39], 0, v[130:131]
	s_mov_b32 m0, s27
	s_nop 0
	global_load_lds_dwordx4 v[228:229], off
	s_waitcnt vmcnt(8)
	s_waitcnt lgkmcnt(0)
	s_barrier
	s_waitcnt lgkmcnt(0)
	v_mfma_f32_16x16x32_bf16 v[124:127], v[144:147], v[176:179], v[124:127]
	v_mfma_f32_16x16x32_bf16 v[120:123], v[152:155], v[176:179], v[120:123]
	v_mfma_f32_16x16x32_bf16 v[108:111], v[144:147], v[184:187], v[108:111]
	v_mfma_f32_16x16x32_bf16 v[104:107], v[152:155], v[184:187], v[104:107]
	v_mfma_f32_16x16x32_bf16 v[92:95], v[144:147], v[192:195], v[92:95]
	v_mfma_f32_16x16x32_bf16 v[88:91], v[152:155], v[192:195], v[88:91]
	v_mfma_f32_16x16x32_bf16 v[76:79], v[144:147], v[212:215], v[76:79]
	v_mfma_f32_16x16x32_bf16 v[72:75], v[152:155], v[212:215], v[72:75]
	v_mfma_f32_16x16x32_bf16 v[124:127], v[148:151], v[180:183], v[124:127]
	v_mfma_f32_16x16x32_bf16 v[120:123], v[156:159], v[180:183], v[120:123]
	v_mfma_f32_16x16x32_bf16 v[108:111], v[148:151], v[188:191], v[108:111]
	v_mfma_f32_16x16x32_bf16 v[104:107], v[156:159], v[188:191], v[104:107]
	v_mfma_f32_16x16x32_bf16 v[92:95], v[148:151], v[196:199], v[92:95]
	v_mfma_f32_16x16x32_bf16 v[88:91], v[156:159], v[196:199], v[88:91]
	v_mfma_f32_16x16x32_bf16 v[76:79], v[148:151], v[216:219], v[76:79]
	v_mfma_f32_16x16x32_bf16 v[72:75], v[156:159], v[216:219], v[72:75]
	v_mfma_f32_16x16x32_bf16 v[116:119], v[160:163], v[176:179], v[116:119]
	v_mfma_f32_16x16x32_bf16 v[112:115], v[168:171], v[176:179], v[112:115]
	v_mfma_f32_16x16x32_bf16 v[100:103], v[160:163], v[184:187], v[100:103]
	v_mfma_f32_16x16x32_bf16 v[96:99], v[168:171], v[184:187], v[96:99]
	v_mfma_f32_16x16x32_bf16 v[84:87], v[160:163], v[192:195], v[84:87]
	v_mfma_f32_16x16x32_bf16 v[80:83], v[168:171], v[192:195], v[80:83]
	v_mfma_f32_16x16x32_bf16 v[68:71], v[160:163], v[212:215], v[68:71]
	v_mfma_f32_16x16x32_bf16 v[64:67], v[168:171], v[212:215], v[64:67]
	v_mfma_f32_16x16x32_bf16 v[116:119], v[164:167], v[180:183], v[116:119]
	v_mfma_f32_16x16x32_bf16 v[112:115], v[172:175], v[180:183], v[112:115]
	v_mfma_f32_16x16x32_bf16 v[100:103], v[164:167], v[188:191], v[100:103]
	v_mfma_f32_16x16x32_bf16 v[96:99], v[172:175], v[188:191], v[96:99]
	v_mfma_f32_16x16x32_bf16 v[84:87], v[164:167], v[196:199], v[84:87]
	v_mfma_f32_16x16x32_bf16 v[80:83], v[172:175], v[196:199], v[80:83]
	v_mfma_f32_16x16x32_bf16 v[68:71], v[164:167], v[216:219], v[68:71]
	v_mfma_f32_16x16x32_bf16 v[64:67], v[172:175], v[216:219], v[64:67]
	s_barrier
; #define PG8_STAGE(bufoff, gbase, voff) do { _Pragma("unroll") for (int _i = 0; _i < 2; ++_i) \
;         __builtin_amdgcn_global_load_lds((const unsigned*)((const char*)(gbase) + (voff)[_i]), (LAS unsigned*)(lds + (bufoff) + ldsw + _i * 8192), 16, 0, 0); } while (0)
; #define PG8_LDA(dst, b, h) do { _Pragma("unroll") for (int m = 0; m < 4; ++m) _Pragma("unroll") for (int k = 0; k < 2; ++k) dst[m][k] = *(const LAS bf16x8*)(lds + PG8_SA(b, h) + aoff + m * 2048 + k * 1024); } while (0)
; #define PG8_BAR __builtin_amdgcn_s_barrier()
; template <class Epi, class Sched, bool ALIGN_EPI = true, bool SP2 = true, class Pre = NoPre>
; __device__ __forceinline__ void gemm_phase(LAS unsigned char* lds, const Gemm g, const Sched& S, const Epi& E, const Pre& pre = Pre()) {
;     ...
;             PG8_LDA(At, 1, 1); PG8_STAGE(PG8_SB(1, 0), b3, voffB); PG8_STAGE(PG8_SB(1, 1), b3 + hsB, voffB); PG8_STAGE(PG8_SA(1, 0), a3, voffA);
;             PG8_WAIT_V(8); PG8_WAIT_L(0); PG8_BAR; PG8_MMA(1, 0, At, B0); PG8_MMA(1, 1, At, B1); PG8_BAR; PG8_SCHED;
;             } else {
;             PG8_LDB(B0, 0, 0); PG8_SCHED; PG8_LDA(At, 0, 0); PG8_STAGE(PG8_SA(1, 1), a1 + hsA, voffA);
;             PG8_WAIT_L(8); PG8_BAR; PG8_WAIT_L(0); PG8_MMA(0, 0, At, B0); PG8_BAR; PG8_SCHED;
;             PG8_LDB(B1, 0, 1); PG8_STAGE(PG8_SB(0, 0), b2, voffB);
;             PG8_BAR; PG8_WAIT_L(0); PG8_MMA(0, 1, At, B1); PG8_BAR;
;             PG8_LDA(At, 0, 1); PG8_STAGE(PG8_SA(0, 0), a2, voffA);
;             PG8_BAR; PG8_WAIT_L(0); PG8_MMA(1, 0, At, B0); PG8_BAR; PG8_SCHED;
;             PG8_STAGE(PG8_SB(0, 1), b2 + hsB, voffB);
;             PG8_WAIT_V(6); PG8_BAR; PG8_MMA(1, 1, At, B1); PG8_BAR;
;             PG8_LDB(B0, 1, 0); PG8_SCHED; PG8_LDA(At, 1, 0); PG8_STAGE(PG8_SA(0, 1), a2 + hsA, voffA);
;             PG8_WAIT_L(8); PG8_BAR; PG8_WAIT_L(0); PG8_MMA(0, 0, At, B0); PG8_BAR; PG8_SCHED;
;             PG8_LDB(B1, 1, 1); PG8_STAGE(PG8_SB(1, 0), b3, voffB);
;             PG8_BAR; PG8_WAIT_L(0); PG8_MMA(0, 1, At, B1); PG8_BAR;
;             PG8_LDA(At, 1, 1); PG8_STAGE(PG8_SA(1, 0), a3, voffA);
;             PG8_BAR; PG8_WAIT_L(0); PG8_MMA(1, 0, At, B0); PG8_BAR; PG8_SCHED;
;             PG8_STAGE(PG8_SB(1, 1), b3 + hsB, voffB);
;             PG8_WAIT_V(6); PG8_BAR; PG8_MMA(1, 1, At, B1); PG8_BAR;
;             }
;         }
;         if constexpr (ALIGN_EPI) { if (wr == 0) PG8_BAR; }
	s_add_i32 s38, s80, s7
	v_lshl_add_u64 v[220:221], v[220:221], 0, s[50:51]
	s_mov_b32 m0, s38
	ds_read_b128 v[176:179], v143 offset:49152
	ds_read_b128 v[180:183], v143 offset:50176
	ds_read_b128 v[184:187], v143 offset:51200
	ds_read_b128 v[188:191], v143 offset:52224
	ds_read_b128 v[192:195], v143 offset:53248
	ds_read_b128 v[196:199], v143 offset:54272
	ds_read_b128 v[212:215], v143 offset:55296
	ds_read_b128 v[216:219], v143 offset:56320
	global_load_lds_dwordx4 v[220:221], off
	s_add_i32 m0, s38, 0x2000
	s_add_u32 s10, s10, 0x40080
	v_lshl_add_u64 v[220:221], v[222:223], 0, s[50:51]
	s_addc_u32 s11, s11, 0
	s_add_i32 s38, s81, s7
	global_load_lds_dwordx4 v[220:221], off
	v_lshl_add_u64 v[220:221], s[10:11], 0, v[200:201]
	s_mov_b32 m0, s38
	s_nop 0
	global_load_lds_dwordx4 v[220:221], off
	v_lshl_add_u64 v[220:221], s[10:11], 0, v[128:129]
	s_add_i32 m0, s38, 0x2000
	s_nop 0
	global_load_lds_dwordx4 v[220:221], off
	v_lshl_add_u64 v[220:221], v[224:225], 0, s[50:51]
	s_mov_b32 m0, s29
	s_nop 0
	global_load_lds_dwordx4 v[220:221], off
	v_lshl_add_u64 v[220:221], v[226:227], 0, s[50:51]
	s_mov_b32 m0, s42
	s_nop 0
	global_load_lds_dwordx4 v[220:221], off
	s_waitcnt vmcnt(8)
	s_waitcnt lgkmcnt(0)
	s_barrier
	s_waitcnt lgkmcnt(0)
	v_mfma_f32_16x16x32_bf16 v[60:63], v[144:147], v[176:179], v[60:63]
	v_mfma_f32_16x16x32_bf16 v[56:59], v[152:155], v[176:179], v[56:59]
	v_mfma_f32_16x16x32_bf16 v[52:55], v[144:147], v[184:187], v[52:55]
	v_mfma_f32_16x16x32_bf16 v[44:47], v[152:155], v[184:187], v[44:47]
	v_mfma_f32_16x16x32_bf16 v[36:39], v[144:147], v[192:195], v[36:39]
	v_mfma_f32_16x16x32_bf16 v[28:31], v[152:155], v[192:195], v[28:31]
	v_mfma_f32_16x16x32_bf16 v[16:19], v[144:147], v[212:215], v[16:19]
	v_mfma_f32_16x16x32_bf16 v[8:11], v[152:155], v[212:215], v[8:11]
	v_mfma_f32_16x16x32_bf16 v[60:63], v[148:151], v[180:183], v[60:63]
	v_mfma_f32_16x16x32_bf16 v[56:59], v[156:159], v[180:183], v[56:59]
	v_mfma_f32_16x16x32_bf16 v[52:55], v[148:151], v[188:191], v[52:55]
	v_mfma_f32_16x16x32_bf16 v[44:47], v[156:159], v[188:191], v[44:47]
	v_mfma_f32_16x16x32_bf16 v[36:39], v[148:151], v[196:199], v[36:39]
	v_mfma_f32_16x16x32_bf16 v[28:31], v[156:159], v[196:199], v[28:31]
	v_mfma_f32_16x16x32_bf16 v[16:19], v[148:151], v[216:219], v[16:19]
	v_mfma_f32_16x16x32_bf16 v[8:11], v[156:159], v[216:219], v[8:11]
	v_mfma_f32_16x16x32_bf16 v[48:51], v[160:163], v[176:179], v[48:51]
	v_mfma_f32_16x16x32_bf16 v[40:43], v[168:171], v[176:179], v[40:43]
	v_mfma_f32_16x16x32_bf16 v[32:35], v[160:163], v[184:187], v[32:35]
	v_mfma_f32_16x16x32_bf16 v[24:27], v[168:171], v[184:187], v[24:27]
	v_mfma_f32_16x16x32_bf16 v[20:23], v[160:163], v[192:195], v[20:23]
	v_mfma_f32_16x16x32_bf16 v[12:15], v[168:171], v[192:195], v[12:15]
	v_mfma_f32_16x16x32_bf16 v[4:7], v[160:163], v[212:215], v[4:7]
	v_mfma_f32_16x16x32_bf16 v[0:3], v[168:171], v[212:215], v[0:3]
	v_mfma_f32_16x16x32_bf16 v[48:51], v[164:167], v[180:183], v[48:51]
	v_mfma_f32_16x16x32_bf16 v[40:43], v[172:175], v[180:183], v[40:43]
	v_mfma_f32_16x16x32_bf16 v[32:35], v[164:167], v[188:191], v[32:35]
	v_mfma_f32_16x16x32_bf16 v[24:27], v[172:175], v[188:191], v[24:27]
	v_mfma_f32_16x16x32_bf16 v[20:23], v[164:167], v[196:199], v[20:23]
	v_mfma_f32_16x16x32_bf16 v[12:15], v[172:175], v[196:199], v[12:15]
	v_mfma_f32_16x16x32_bf16 v[4:7], v[164:167], v[216:219], v[4:7]
	v_mfma_f32_16x16x32_bf16 v[0:3], v[172:175], v[216:219], v[0:3]
	s_barrier
	s_add_i32 s58, s58, 2
	s_add_u32 s47, s47, 0x100
	s_addc_u32 s53, s53, 0
	s_add_u32 s30, s30, 0x100
	s_addc_u32 s31, s31, 0
	s_cmp_gt_u32 s58, 13
	s_cbranch_scc0 .LBB0_858
	v_readlane_b32 s80, v255, 28
	v_readlane_b32 s82, v255, 30
	s_and_b64 vcc, exec, s[12:13]
	s_mov_b32 s14, s82
	v_readlane_b32 s81, v255, 29
	v_readlane_b32 s83, v255, 31
	s_cbranch_vccz .LBB0_861
	s_barrier

; #define PG8_STAGE(bufoff, gbase, voff) do { _Pragma("unroll") for (int _i = 0; _i < 2; ++_i) \
;         __builtin_amdgcn_global_load_lds((const unsigned*)((const char*)(gbase) + (voff)[_i]), (LAS unsigned*)(lds + (bufoff) + ldsw + _i * 8192), 16, 0, 0); } while (0)
; #define PG8_LDA(dst, b, h) do { _Pragma("unroll") for (int m = 0; m < 4; ++m) _Pragma("unroll") for (int k = 0; k < 2; ++k) dst[m][k] = *(const LAS bf16x8*)(lds + PG8_SA(b, h) + aoff + m * 2048 + k * 1024); } while (0)
; #define PG8_LDB(dst, b, h) do { _Pragma("unroll") for (int n = 0; n < 2; ++n) _Pragma("unroll") for (int k = 0; k < 2; ++k) dst[n][k] = *(const LAS bf16x8*)(lds + PG8_SB(b, h) + boff + n * 2048 + k * 1024); } while (0)
; #define PG8_MMA(ai, bj, At, Bt) do { __builtin_amdgcn_s_setprio(1); _Pragma("unroll") for (int m = 0; m < 4; ++m) _Pragma("unroll") for (int n = 0; n < 2; ++n) _Pragma("unroll") for (int k = 0; k < 2; ++k) \
;         acc[ai][bj][m][n] = __builtin_amdgcn_mfma_f32_16x16x32_bf16(Bt[n][k], At[m][k], acc[ai][bj][m][n], 0, 0, 0); __builtin_amdgcn_s_setprio(0); } while (0)
; #define PG8_WAIT_V(n) asm volatile("s_waitcnt vmcnt(" #n ")" ::: "memory")
; #define PG8_WAIT_L(n) asm volatile("s_waitcnt lgkmcnt(" #n ")" ::: "memory")
; #define PG8_BAR __builtin_amdgcn_s_barrier()
; template <class Epi, class Sched, bool ALIGN_EPI = true, bool SP2 = true, class Pre = NoPre>
; __device__ __forceinline__ void gemm_phase(LAS unsigned char* lds, const Gemm g, const Sched& S, const Epi& E, const Pre& pre = Pre()) {
;     ...
;             const bool last = (t == nt - 2);
;             const char* a1 = cA + (size_t)(t + 1) * kstep;
;             const char* a2 = last ? nA : cA + (size_t)(t + 2) * kstep; const char* b2 = last ? nB : cB + (size_t)(t + 2) * kstep;
;             const char* a3 = a2 + kstep; const char* b3 = b2 + kstep;
;             if constexpr (SP2) {
;             PG8_LDB(B0, 0, 0); PG8_LDB(B1, 0, 1); PG8_SCHED; PG8_LDA(At, 0, 0); PG8_STAGE(PG8_SA(1, 1), a1 + hsA, voffA);
;             PG8_WAIT_V(8); PG8_WAIT_L(0); PG8_BAR; PG8_MMA(0, 0, At, B0); PG8_MMA(0, 1, At, B1); PG8_BAR; PG8_SCHED;
;             PG8_LDA(At, 0, 1); PG8_STAGE(PG8_SB(0, 0), b2, voffB); PG8_STAGE(PG8_SB(0, 1), b2 + hsB, voffB); PG8_STAGE(PG8_SA(0, 0), a2, voffA);
;             PG8_WAIT_V(8); PG8_WAIT_L(0); PG8_BAR; PG8_MMA(1, 0, At, B0); PG8_MMA(1, 1, At, B1); PG8_BAR; PG8_SCHED;
.LBB0_936:
	s_add_u32 s80, s44, 0xfff00080
	s_addc_u32 s81, s45, -1
	s_add_i32 s87, 0, 0x10000
	s_cmp_eq_u32 s58, 60
	s_cselect_b32 s83, s23, s81
	s_cselect_b32 s82, s25, s80
	s_cselect_b32 s81, s21, s47
	s_cselect_b32 s80, s43, s46
	s_add_i32 s96, 0, 0x14000
	v_add_u32_e32 v112, s87, v235
	v_add_u32_e32 v156, s96, v235
	ds_read_b128 v[80:83], v112
	ds_read_b128 v[88:91], v112 offset:1024
	ds_read_b128 v[104:107], v112 offset:2048
	ds_read_b128 v[112:115], v112 offset:3072
	ds_read_b128 v[124:127], v156
	ds_read_b128 v[132:135], v156 offset:1024
	ds_read_b128 v[144:147], v156 offset:2048
	ds_read_b128 v[156:159], v156 offset:3072
	v_lshl_add_u64 v[198:199], s[44:45], 0, v[196:197]
	s_add_i32 m0, s8, 0xc000
	ds_read_b128 v[160:163], v245
	ds_read_b128 v[164:167], v245 offset:1024
	ds_read_b128 v[168:171], v245 offset:2048
	ds_read_b128 v[172:175], v245 offset:3072
	ds_read_b128 v[176:179], v245 offset:4096
	ds_read_b128 v[180:183], v245 offset:5120
	ds_read_b128 v[184:187], v245 offset:6144
	ds_read_b128 v[212:215], v245 offset:7168
	global_load_lds_dwordx4 v[198:199], off
	v_lshl_add_u64 v[198:199], s[44:45], 0, v[194:195]
	s_add_i32 m0, s8, 0xe000
	s_nop 0
	global_load_lds_dwordx4 v[198:199], off
	s_waitcnt vmcnt(8)
	s_waitcnt lgkmcnt(0)
	s_barrier
	s_waitcnt lgkmcnt(0)
	v_mfma_f32_16x16x32_bf16 v[152:155], v[80:83], v[160:163], v[152:155]
	v_mfma_f32_16x16x32_bf16 v[148:151], v[104:107], v[160:163], v[148:151]
	v_mfma_f32_16x16x32_bf16 v[128:131], v[80:83], v[168:171], v[128:131]
	v_mfma_f32_16x16x32_bf16 v[120:123], v[104:107], v[168:171], v[120:123]
	v_mfma_f32_16x16x32_bf16 v[100:103], v[80:83], v[176:179], v[100:103]
	v_mfma_f32_16x16x32_bf16 v[96:99], v[104:107], v[176:179], v[96:99]
	v_mfma_f32_16x16x32_bf16 v[76:79], v[80:83], v[184:187], v[76:79]
	v_mfma_f32_16x16x32_bf16 v[72:75], v[104:107], v[184:187], v[72:75]
	v_mfma_f32_16x16x32_bf16 v[152:155], v[88:91], v[164:167], v[152:155]
	v_mfma_f32_16x16x32_bf16 v[148:151], v[112:115], v[164:167], v[148:151]
	v_mfma_f32_16x16x32_bf16 v[128:131], v[88:91], v[172:175], v[128:131]
	v_mfma_f32_16x16x32_bf16 v[120:123], v[112:115], v[172:175], v[120:123]
	v_mfma_f32_16x16x32_bf16 v[100:103], v[88:91], v[180:183], v[100:103]
	v_mfma_f32_16x16x32_bf16 v[96:99], v[112:115], v[180:183], v[96:99]
	v_mfma_f32_16x16x32_bf16 v[76:79], v[88:91], v[212:215], v[76:79]
	v_mfma_f32_16x16x32_bf16 v[72:75], v[112:115], v[212:215], v[72:75]
	v_mfma_f32_16x16x32_bf16 v[140:143], v[124:127], v[160:163], v[140:143]
	v_mfma_f32_16x16x32_bf16 v[136:139], v[144:147], v[160:163], v[136:139]
	v_mfma_f32_16x16x32_bf16 v[116:119], v[124:127], v[168:171], v[116:119]
	v_mfma_f32_16x16x32_bf16 v[108:111], v[144:147], v[168:171], v[108:111]
	v_mfma_f32_16x16x32_bf16 v[92:95], v[124:127], v[176:179], v[92:95]
	v_mfma_f32_16x16x32_bf16 v[84:87], v[144:147], v[176:179], v[84:87]
	v_mfma_f32_16x16x32_bf16 v[68:71], v[124:127], v[184:187], v[68:71]
	v_mfma_f32_16x16x32_bf16 v[64:67], v[144:147], v[184:187], v[64:67]
	v_mfma_f32_16x16x32_bf16 v[140:143], v[132:135], v[164:167], v[140:143]
	v_mfma_f32_16x16x32_bf16 v[136:139], v[156:159], v[164:167], v[136:139]
	v_mfma_f32_16x16x32_bf16 v[116:119], v[132:135], v[172:175], v[116:119]
	v_mfma_f32_16x16x32_bf16 v[108:111], v[156:159], v[172:175], v[108:111]
	v_mfma_f32_16x16x32_bf16 v[92:95], v[132:135], v[180:183], v[92:95]
	v_mfma_f32_16x16x32_bf16 v[84:87], v[156:159], v[180:183], v[84:87]
	v_mfma_f32_16x16x32_bf16 v[68:71], v[132:135], v[212:215], v[68:71]
	v_mfma_f32_16x16x32_bf16 v[64:67], v[156:159], v[212:215], v[64:67]
	s_barrier
	s_add_i32 s87, s87, s7
	v_lshl_add_u64 v[198:199], s[80:81], 0, v[200:201]
	s_mov_b32 m0, s87
	ds_read_b128 v[160:163], v245 offset:16384
	ds_read_b128 v[164:167], v245 offset:17408
	ds_read_b128 v[168:171], v245 offset:18432
	ds_read_b128 v[172:175], v245 offset:19456
	ds_read_b128 v[176:179], v245 offset:20480
	ds_read_b128 v[180:183], v245 offset:21504
	ds_read_b128 v[184:187], v245 offset:22528
	ds_read_b128 v[212:215], v245 offset:23552
	global_load_lds_dwordx4 v[198:199], off
	s_add_i32 m0, s87, 0x2000
	s_add_u32 s92, s80, 0x100000
	v_lshl_add_u64 v[216:217], s[80:81], 0, v[192:193]
	s_addc_u32 s93, s81, 0
	s_add_i32 s87, s96, s7
	global_load_lds_dwordx4 v[216:217], off
	v_lshl_add_u64 v[218:219], s[92:93], 0, v[200:201]
	s_mov_b32 m0, s87
	v_lshl_add_u64 v[220:221], s[82:83], 0, v[190:191]
	global_load_lds_dwordx4 v[218:219], off
	v_lshl_add_u64 v[218:219], s[92:93], 0, v[192:193]
	s_add_i32 m0, s87, 0x2000
	s_nop 0
	global_load_lds_dwordx4 v[218:219], off
	v_lshl_add_u64 v[218:219], s[82:83], 0, v[188:189]
	s_mov_b32 m0, s8
	s_nop 0
	global_load_lds_dwordx4 v[218:219], off
	s_mov_b32 m0, s9
	s_nop 0
	global_load_lds_dwordx4 v[220:221], off
	s_waitcnt vmcnt(8)
	s_waitcnt lgkmcnt(0)
	s_barrier
; #define PG8_STAGE(bufoff, gbase, voff) do { _Pragma("unroll") for (int _i = 0; _i < 2; ++_i) \
;         __builtin_amdgcn_global_load_lds((const unsigned*)((const char*)(gbase) + (voff)[_i]), (LAS unsigned*)(lds + (bufoff) + ldsw + _i * 8192), 16, 0, 0); } while (0)
; #define PG8_LDA(dst, b, h) do { _Pragma("unroll") for (int m = 0; m < 4; ++m) _Pragma("unroll") for (int k = 0; k < 2; ++k) dst[m][k] = *(const LAS bf16x8*)(lds + PG8_SA(b, h) + aoff + m * 2048 + k * 1024); } while (0)
; #define PG8_LDB(dst, b, h) do { _Pragma("unroll") for (int n = 0; n < 2; ++n) _Pragma("unroll") for (int k = 0; k < 2; ++k) dst[n][k] = *(const LAS bf16x8*)(lds + PG8_SB(b, h) + boff + n * 2048 + k * 1024); } while (0)
; #define PG8_MMA(ai, bj, At, Bt) do { __builtin_amdgcn_s_setprio(1); _Pragma("unroll") for (int m = 0; m < 4; ++m) _Pragma("unroll") for (int n = 0; n < 2; ++n) _Pragma("unroll") for (int k = 0; k < 2; ++k) \
;         acc[ai][bj][m][n] = __builtin_amdgcn_mfma_f32_16x16x32_bf16(Bt[n][k], At[m][k], acc[ai][bj][m][n], 0, 0, 0); __builtin_amdgcn_s_setprio(0); } while (0)
; #define PG8_WAIT_V(n) asm volatile("s_waitcnt vmcnt(" #n ")" ::: "memory")
; #define PG8_WAIT_L(n) asm volatile("s_waitcnt lgkmcnt(" #n ")" ::: "memory")
; #define PG8_BAR __builtin_amdgcn_s_barrier()
; #define PG8_SCHED __builtin_amdgcn_sched_barrier(0)
; template <class Epi, class Sched, bool ALIGN_EPI = true, bool SP2 = true, class Pre = NoPre>
; __device__ __forceinline__ void gemm_phase(LAS unsigned char* lds, const Gemm g, const Sched& S, const Epi& E, const Pre& pre = Pre()) {
;     ...
;             PG8_WAIT_V(8); PG8_WAIT_L(0); PG8_BAR; PG8_MMA(1, 0, At, B0); PG8_MMA(1, 1, At, B1); PG8_BAR; PG8_SCHED;
;             PG8_LDB(B0, 1, 0); PG8_LDB(B1, 1, 1); PG8_SCHED; PG8_LDA(At, 1, 0); PG8_STAGE(PG8_SA(0, 1), a2 + hsA, voffA);
;             PG8_WAIT_V(8); PG8_WAIT_L(0); PG8_BAR; PG8_MMA(0, 0, At, B0); PG8_MMA(0, 1, At, B1); PG8_BAR; PG8_SCHED;
	s_waitcnt lgkmcnt(0)
	v_mfma_f32_16x16x32_bf16 v[60:63], v[80:83], v[160:163], v[60:63]
	v_mfma_f32_16x16x32_bf16 v[56:59], v[104:107], v[160:163], v[56:59]
	v_mfma_f32_16x16x32_bf16 v[44:47], v[80:83], v[168:171], v[44:47]
	v_mfma_f32_16x16x32_bf16 v[40:43], v[104:107], v[168:171], v[40:43]
	v_mfma_f32_16x16x32_bf16 v[28:31], v[80:83], v[176:179], v[28:31]
	v_mfma_f32_16x16x32_bf16 v[24:27], v[104:107], v[176:179], v[24:27]
	v_mfma_f32_16x16x32_bf16 v[12:15], v[80:83], v[184:187], v[12:15]
	v_mfma_f32_16x16x32_bf16 v[8:11], v[104:107], v[184:187], v[8:11]
	v_mfma_f32_16x16x32_bf16 v[60:63], v[88:91], v[164:167], v[60:63]
	v_mfma_f32_16x16x32_bf16 v[56:59], v[112:115], v[164:167], v[56:59]
	v_mfma_f32_16x16x32_bf16 v[44:47], v[88:91], v[172:175], v[44:47]
	v_mfma_f32_16x16x32_bf16 v[40:43], v[112:115], v[172:175], v[40:43]
	v_mfma_f32_16x16x32_bf16 v[28:31], v[88:91], v[180:183], v[28:31]
	v_mfma_f32_16x16x32_bf16 v[24:27], v[112:115], v[180:183], v[24:27]
	v_mfma_f32_16x16x32_bf16 v[12:15], v[88:91], v[212:215], v[12:15]
	v_mfma_f32_16x16x32_bf16 v[8:11], v[112:115], v[212:215], v[8:11]
	v_mfma_f32_16x16x32_bf16 v[52:55], v[124:127], v[160:163], v[52:55]
	v_mfma_f32_16x16x32_bf16 v[48:51], v[144:147], v[160:163], v[48:51]
	v_mfma_f32_16x16x32_bf16 v[36:39], v[124:127], v[168:171], v[36:39]
	v_mfma_f32_16x16x32_bf16 v[32:35], v[144:147], v[168:171], v[32:35]
	v_mfma_f32_16x16x32_bf16 v[20:23], v[124:127], v[176:179], v[20:23]
	v_mfma_f32_16x16x32_bf16 v[16:19], v[144:147], v[176:179], v[16:19]
	v_mfma_f32_16x16x32_bf16 v[4:7], v[124:127], v[184:187], v[4:7]
	v_mfma_f32_16x16x32_bf16 v[0:3], v[144:147], v[184:187], v[0:3]
	v_mfma_f32_16x16x32_bf16 v[52:55], v[132:135], v[164:167], v[52:55]
	v_mfma_f32_16x16x32_bf16 v[48:51], v[156:159], v[164:167], v[48:51]
	v_mfma_f32_16x16x32_bf16 v[36:39], v[132:135], v[172:175], v[36:39]
	v_mfma_f32_16x16x32_bf16 v[32:35], v[156:159], v[172:175], v[32:35]
	v_mfma_f32_16x16x32_bf16 v[20:23], v[132:135], v[180:183], v[20:23]
	v_mfma_f32_16x16x32_bf16 v[16:19], v[156:159], v[180:183], v[16:19]
	v_mfma_f32_16x16x32_bf16 v[4:7], v[132:135], v[212:215], v[4:7]
	v_mfma_f32_16x16x32_bf16 v[0:3], v[156:159], v[212:215], v[0:3]
	s_barrier
	s_add_i32 s87, 0, 0x18000
	s_add_i32 s92, 0, 0x1c000
	v_add_u32_e32 v112, s87, v235
	v_add_u32_e32 v156, s92, v235
	ds_read_b128 v[80:83], v112
	ds_read_b128 v[88:91], v112 offset:1024
	ds_read_b128 v[104:107], v112 offset:2048
	ds_read_b128 v[112:115], v112 offset:3072
	ds_read_b128 v[124:127], v156
	ds_read_b128 v[132:135], v156 offset:1024
	ds_read_b128 v[144:147], v156 offset:2048
	ds_read_b128 v[156:159], v156 offset:3072
	s_add_u32 s82, s82, 0x100000
	s_addc_u32 s83, s83, 0
	s_mov_b32 m0, s15
	v_lshl_add_u64 v[222:223], s[82:83], 0, v[188:189]
	ds_read_b128 v[160:163], v245 offset:32768
	ds_read_b128 v[164:167], v245 offset:33792
	ds_read_b128 v[168:171], v245 offset:34816
	ds_read_b128 v[172:175], v245 offset:35840
	ds_read_b128 v[176:179], v245 offset:36864
	ds_read_b128 v[180:183], v245 offset:37888
	ds_read_b128 v[184:187], v245 offset:38912
	ds_read_b128 v[212:215], v245 offset:39936
	global_load_lds_dwordx4 v[222:223], off
	v_lshl_add_u64 v[222:223], s[82:83], 0, v[190:191]
	s_mov_b32 m0, s27
	s_nop 0
	global_load_lds_dwordx4 v[222:223], off
	s_waitcnt vmcnt(8)
	s_waitcnt lgkmcnt(0)
	s_barrier
	s_waitcnt lgkmcnt(0)
	v_mfma_f32_16x16x32_bf16 v[152:155], v[80:83], v[160:163], v[152:155]
	v_mfma_f32_16x16x32_bf16 v[148:151], v[104:107], v[160:163], v[148:151]
	v_mfma_f32_16x16x32_bf16 v[128:131], v[80:83], v[168:171], v[128:131]
	v_mfma_f32_16x16x32_bf16 v[120:123], v[104:107], v[168:171], v[120:123]
	v_mfma_f32_16x16x32_bf16 v[100:103], v[80:83], v[176:179], v[100:103]
	v_mfma_f32_16x16x32_bf16 v[96:99], v[104:107], v[176:179], v[96:99]
	v_mfma_f32_16x16x32_bf16 v[76:79], v[80:83], v[184:187], v[76:79]
	v_mfma_f32_16x16x32_bf16 v[72:75], v[104:107], v[184:187], v[72:75]
	v_mfma_f32_16x16x32_bf16 v[152:155], v[88:91], v[164:167], v[152:155]
	v_mfma_f32_16x16x32_bf16 v[148:151], v[112:115], v[164:167], v[148:151]
	v_mfma_f32_16x16x32_bf16 v[128:131], v[88:91], v[172:175], v[128:131]
	v_mfma_f32_16x16x32_bf16 v[120:123], v[112:115], v[172:175], v[120:123]
	v_mfma_f32_16x16x32_bf16 v[100:103], v[88:91], v[180:183], v[100:103]
	v_mfma_f32_16x16x32_bf16 v[96:99], v[112:115], v[180:183], v[96:99]
	v_mfma_f32_16x16x32_bf16 v[76:79], v[88:91], v[212:215], v[76:79]
	v_mfma_f32_16x16x32_bf16 v[72:75], v[112:115], v[212:215], v[72:75]
	v_mfma_f32_16x16x32_bf16 v[140:143], v[124:127], v[160:163], v[140:143]
	v_mfma_f32_16x16x32_bf16 v[136:139], v[144:147], v[160:163], v[136:139]
	v_mfma_f32_16x16x32_bf16 v[116:119], v[124:127], v[168:171], v[116:119]
	v_mfma_f32_16x16x32_bf16 v[108:111], v[144:147], v[168:171], v[108:111]
	v_mfma_f32_16x16x32_bf16 v[92:95], v[124:127], v[176:179], v[92:95]
	v_mfma_f32_16x16x32_bf16 v[84:87], v[144:147], v[176:179], v[84:87]
	v_mfma_f32_16x16x32_bf16 v[68:71], v[124:127], v[184:187], v[68:71]
	v_mfma_f32_16x16x32_bf16 v[64:67], v[144:147], v[184:187], v[64:67]
	v_mfma_f32_16x16x32_bf16 v[140:143], v[132:135], v[164:167], v[140:143]
	v_mfma_f32_16x16x32_bf16 v[136:139], v[156:159], v[164:167], v[136:139]
	v_mfma_f32_16x16x32_bf16 v[116:119], v[132:135], v[172:175], v[116:119]
	v_mfma_f32_16x16x32_bf16 v[108:111], v[156:159], v[172:175], v[108:111]
	v_mfma_f32_16x16x32_bf16 v[92:95], v[132:135], v[180:183], v[92:95]
	v_mfma_f32_16x16x32_bf16 v[84:87], v[156:159], v[180:183], v[84:87]
	v_mfma_f32_16x16x32_bf16 v[68:71], v[132:135], v[212:215], v[68:71]
	v_mfma_f32_16x16x32_bf16 v[64:67], v[156:159], v[212:215], v[64:67]
	s_barrier
; #define PG8_STAGE(bufoff, gbase, voff) do { _Pragma("unroll") for (int _i = 0; _i < 2; ++_i) \
;         __builtin_amdgcn_global_load_lds((const unsigned*)((const char*)(gbase) + (voff)[_i]), (LAS unsigned*)(lds + (bufoff) + ldsw + _i * 8192), 16, 0, 0); } while (0)
; #define PG8_LDA(dst, b, h) do { _Pragma("unroll") for (int m = 0; m < 4; ++m) _Pragma("unroll") for (int k = 0; k < 2; ++k) dst[m][k] = *(const LAS bf16x8*)(lds + PG8_SA(b, h) + aoff + m * 2048 + k * 1024); } while (0)
; #define PG8_BAR __builtin_amdgcn_s_barrier()
; template <class Epi, class Sched, bool ALIGN_EPI = true, bool SP2 = true, class Pre = NoPre>
; __device__ __forceinline__ void gemm_phase(LAS unsigned char* lds, const Gemm g, const Sched& S, const Epi& E, const Pre& pre = Pre()) {
;     ...
;             PG8_LDA(At, 1, 1); PG8_STAGE(PG8_SB(1, 0), b3, voffB); PG8_STAGE(PG8_SB(1, 1), b3 + hsB, voffB); PG8_STAGE(PG8_SA(1, 0), a3, voffA);
;             PG8_WAIT_V(8); PG8_WAIT_L(0); PG8_BAR; PG8_MMA(1, 0, At, B0); PG8_MMA(1, 1, At, B1); PG8_BAR; PG8_SCHED;
;             } else {
;             PG8_LDB(B0, 0, 0); PG8_SCHED; PG8_LDA(At, 0, 0); PG8_STAGE(PG8_SA(1, 1), a1 + hsA, voffA);
;             PG8_WAIT_L(8); PG8_BAR; PG8_WAIT_L(0); PG8_MMA(0, 0, At, B0); PG8_BAR; PG8_SCHED;
;             PG8_LDB(B1, 0, 1); PG8_STAGE(PG8_SB(0, 0), b2, voffB);
;             PG8_BAR; PG8_WAIT_L(0); PG8_MMA(0, 1, At, B1); PG8_BAR;
;             PG8_LDA(At, 0, 1); PG8_STAGE(PG8_SA(0, 0), a2, voffA);
;             PG8_BAR; PG8_WAIT_L(0); PG8_MMA(1, 0, At, B0); PG8_BAR; PG8_SCHED;
;             PG8_STAGE(PG8_SB(0, 1), b2 + hsB, voffB);
;             PG8_WAIT_V(6); PG8_BAR; PG8_MMA(1, 1, At, B1); PG8_BAR;
;             PG8_LDB(B0, 1, 0); PG8_SCHED; PG8_LDA(At, 1, 0); PG8_STAGE(PG8_SA(0, 1), a2 + hsA, voffA);
;             PG8_WAIT_L(8); PG8_BAR; PG8_WAIT_L(0); PG8_MMA(0, 0, At, B0); PG8_BAR; PG8_SCHED;
;             PG8_LDB(B1, 1, 1); PG8_STAGE(PG8_SB(1, 0), b3, voffB);
;             PG8_BAR; PG8_WAIT_L(0); PG8_MMA(0, 1, At, B1); PG8_BAR;
;             PG8_LDA(At, 1, 1); PG8_STAGE(PG8_SA(1, 0), a3, voffA);
;             PG8_BAR; PG8_WAIT_L(0); PG8_MMA(1, 0, At, B0); PG8_BAR; PG8_SCHED;
;             PG8_STAGE(PG8_SB(1, 1), b3 + hsB, voffB);
;             PG8_WAIT_V(6); PG8_BAR; PG8_MMA(1, 1, At, B1); PG8_BAR;
;             }
;         }
;         if constexpr (ALIGN_EPI) { if (wr == 0) PG8_BAR; }
	s_add_i32 s82, s87, s7
	v_lshl_add_u64 v[198:199], v[198:199], 0, s[50:51]
	s_mov_b32 m0, s82
	ds_read_b128 v[160:163], v245 offset:49152
	ds_read_b128 v[164:167], v245 offset:50176
	ds_read_b128 v[168:171], v245 offset:51200
	ds_read_b128 v[172:175], v245 offset:52224
	ds_read_b128 v[176:179], v245 offset:53248
	ds_read_b128 v[180:183], v245 offset:54272
	ds_read_b128 v[184:187], v245 offset:55296
	ds_read_b128 v[212:215], v245 offset:56320
	global_load_lds_dwordx4 v[198:199], off
	s_add_i32 m0, s82, 0x2000
	s_add_u32 s80, s80, 0x100080
	v_lshl_add_u64 v[198:199], v[216:217], 0, s[50:51]
	s_addc_u32 s81, s81, 0
	s_add_i32 s82, s92, s7
	global_load_lds_dwordx4 v[198:199], off
	v_lshl_add_u64 v[198:199], s[80:81], 0, v[200:201]
	s_mov_b32 m0, s82
	s_nop 0
	global_load_lds_dwordx4 v[198:199], off
	v_lshl_add_u64 v[198:199], s[80:81], 0, v[192:193]
	s_add_i32 m0, s82, 0x2000
	s_nop 0
	global_load_lds_dwordx4 v[198:199], off
	v_lshl_add_u64 v[198:199], v[218:219], 0, s[50:51]
	s_mov_b32 m0, s84
	s_nop 0
	global_load_lds_dwordx4 v[198:199], off
	v_lshl_add_u64 v[198:199], v[220:221], 0, s[50:51]
	s_mov_b32 m0, s85
	s_nop 0
	global_load_lds_dwordx4 v[198:199], off
	s_waitcnt vmcnt(8)
	s_waitcnt lgkmcnt(0)
	s_barrier
	s_waitcnt lgkmcnt(0)
	v_mfma_f32_16x16x32_bf16 v[60:63], v[80:83], v[160:163], v[60:63]
	v_mfma_f32_16x16x32_bf16 v[56:59], v[104:107], v[160:163], v[56:59]
	v_mfma_f32_16x16x32_bf16 v[44:47], v[80:83], v[168:171], v[44:47]
	v_mfma_f32_16x16x32_bf16 v[40:43], v[104:107], v[168:171], v[40:43]
	v_mfma_f32_16x16x32_bf16 v[28:31], v[80:83], v[176:179], v[28:31]
	v_mfma_f32_16x16x32_bf16 v[24:27], v[104:107], v[176:179], v[24:27]
	v_mfma_f32_16x16x32_bf16 v[12:15], v[80:83], v[184:187], v[12:15]
	v_mfma_f32_16x16x32_bf16 v[8:11], v[104:107], v[184:187], v[8:11]
	v_mfma_f32_16x16x32_bf16 v[60:63], v[88:91], v[164:167], v[60:63]
	v_mfma_f32_16x16x32_bf16 v[56:59], v[112:115], v[164:167], v[56:59]
	v_mfma_f32_16x16x32_bf16 v[44:47], v[88:91], v[172:175], v[44:47]
	v_mfma_f32_16x16x32_bf16 v[40:43], v[112:115], v[172:175], v[40:43]
	v_mfma_f32_16x16x32_bf16 v[28:31], v[88:91], v[180:183], v[28:31]
	v_mfma_f32_16x16x32_bf16 v[24:27], v[112:115], v[180:183], v[24:27]
	v_mfma_f32_16x16x32_bf16 v[12:15], v[88:91], v[212:215], v[12:15]
	v_mfma_f32_16x16x32_bf16 v[8:11], v[112:115], v[212:215], v[8:11]
	v_mfma_f32_16x16x32_bf16 v[52:55], v[124:127], v[160:163], v[52:55]
	v_mfma_f32_16x16x32_bf16 v[48:51], v[144:147], v[160:163], v[48:51]
	v_mfma_f32_16x16x32_bf16 v[36:39], v[124:127], v[168:171], v[36:39]
	v_mfma_f32_16x16x32_bf16 v[32:35], v[144:147], v[168:171], v[32:35]
	v_mfma_f32_16x16x32_bf16 v[20:23], v[124:127], v[176:179], v[20:23]
	v_mfma_f32_16x16x32_bf16 v[16:19], v[144:147], v[176:179], v[16:19]
	v_mfma_f32_16x16x32_bf16 v[4:7], v[124:127], v[184:187], v[4:7]
	v_mfma_f32_16x16x32_bf16 v[0:3], v[144:147], v[184:187], v[0:3]
	v_mfma_f32_16x16x32_bf16 v[52:55], v[132:135], v[164:167], v[52:55]
	v_mfma_f32_16x16x32_bf16 v[48:51], v[156:159], v[164:167], v[48:51]
	v_mfma_f32_16x16x32_bf16 v[36:39], v[132:135], v[172:175], v[36:39]
	v_mfma_f32_16x16x32_bf16 v[32:35], v[156:159], v[172:175], v[32:35]
	v_mfma_f32_16x16x32_bf16 v[20:23], v[132:135], v[180:183], v[20:23]
	v_mfma_f32_16x16x32_bf16 v[16:19], v[156:159], v[180:183], v[16:19]
	v_mfma_f32_16x16x32_bf16 v[4:7], v[132:135], v[212:215], v[4:7]
	v_mfma_f32_16x16x32_bf16 v[0:3], v[156:159], v[212:215], v[0:3]
	s_barrier
	s_add_i32 s58, s58, 2
	s_add_u32 s46, s46, 0x100
	s_addc_u32 s47, s47, 0
	s_add_u32 s44, s44, 0x100
	s_addc_u32 s45, s45, 0
	s_cmp_gt_u32 s58, 61
	s_cbranch_scc0 .LBB0_936
	s_and_b64 vcc, exec, s[12:13]
	s_cbranch_vccz .LBB0_939
	s_barrier
